# v18: v15 plus one batched prefetch of the residual-stream rows (16 loads into a scratch register quad) at the start of the PLE epilogue so its serialized per-subtile loads hit cache
# baseline (speedup 1.0000x reference)
; DI unsigned pack2(float lo, float hi) { unsigned r; asm("v_cvt_pk_bf16_f32 %0, %1, %2" : "=v"(r) : "v"(lo), "v"(hi)); return r; }
; DI float sigmoidf_(float x) { return 1.f / (1.f + __expf(-x)); }
; template <int EPI>
; DI void gemm_phase(const GArgs& g, char* smem) {
;     ...
;       for (int mi = 0; mi < 2; ++mi) {
;         const int row = m0 + wave * 32 + mi * 16 + (lane & 15);
;         float ssq = 0.f;
; #pragma unroll
;         for (int ni = 0; ni < 8; ++ni) {
;           const int col = n0 + ni * 16 + (lane >> 4) * 4;
;           const float4 hb = *(const float4*)(g.hsrc + (size_t)row * DM + col);
;           const float4 bb = *(const float4*)(g.bias + col);
;           float4 o;
;           o.x = hb.x + sigmoidf_(acc[mi][ni][0] + bb.x) * acc2[mi][ni][0];
;           o.y = hb.y + sigmoidf_(acc[mi][ni][1] + bb.y) * acc2[mi][ni][1];
;           o.z = hb.z + sigmoidf_(acc[mi][ni][2] + bb.z) * acc2[mi][ni][2];
;           o.w = hb.w + sigmoidf_(acc[mi][ni][3] + bb.w) * acc2[mi][ni][3];
;           *(float4*)((float*)g.C + (size_t)row * DM + col) = o;
;           if (g.hnext) {
;             const float4 wn = *(const float4*)(g.wnext + col);
;             u32x2 hb2; hb2[0] = pack2(o.x * wn.x, o.y * wn.y); hb2[1] = pack2(o.z * wn.z, o.w * wn.w);
;             *(u32x2*)(g.hnext + (size_t)row * DM + col) = hb2;
;             ssq += o.x * o.x + o.y * o.y + o.z * o.z + o.w * o.w;
;           }
.LBB0_1344:
	v_add_u32_e32 v136, s23, v166
	v_or_b32_e32 v130, s17, v167
	v_ashrrev_i32_e32 v137, 31, v136
	v_readlane_b32 s20, v251, 16
	v_lshlrev_b64 v[146:147], 13, v[136:137]
	v_readlane_b32 s21, v251, 17
	v_ashrrev_i32_e32 v131, 31, v130
	v_lshlrev_b64 v[134:135], 2, v[130:131]
	v_lshl_add_u64 v[132:133], s[20:21], 0, v[146:147]
	v_lshl_add_u64 v[138:139], v[132:133], 0, v[134:135]
	v_lshl_add_u64 v[132:133], s[8:9], 0, v[134:135]
	global_load_dwordx4 v[142:145], v[132:133], off
	global_load_dwordx4 v[152:155], v[138:139], off
	global_load_dwordx4 v[232:235], v[138:139], off offset:64
	global_load_dwordx4 v[232:235], v[138:139], off offset:128
	global_load_dwordx4 v[232:235], v[138:139], off offset:192
	global_load_dwordx4 v[232:235], v[138:139], off offset:256
	global_load_dwordx4 v[232:235], v[138:139], off offset:320
	global_load_dwordx4 v[232:235], v[138:139], off offset:384
	global_load_dwordx4 v[232:235], v[138:139], off offset:448
	v_mov_b32_e32 v236, 0x20000
	v_mov_b32_e32 v237, 0
	v_lshl_add_u64 v[236:237], v[138:139], 0, v[236:237]
	global_load_dwordx4 v[232:235], v[236:237], off offset:0
	global_load_dwordx4 v[232:235], v[236:237], off offset:64
	global_load_dwordx4 v[232:235], v[236:237], off offset:128
	global_load_dwordx4 v[232:235], v[236:237], off offset:192
	global_load_dwordx4 v[232:235], v[236:237], off offset:256
	global_load_dwordx4 v[232:235], v[236:237], off offset:320
	global_load_dwordx4 v[232:235], v[236:237], off offset:384
	global_load_dwordx4 v[232:235], v[236:237], off offset:448
	v_lshlrev_b64 v[140:141], 11, v[136:137]
	s_waitcnt vmcnt(0)
	v_add_f32_e32 v0, v122, v142
	v_mul_f32_e32 v0, 0xbfb8aa3b, v0
	v_exp_f32_e32 v122, v0
	v_add_f32_e32 v0, v123, v143
	v_mul_f32_e32 v0, 0xbfb8aa3b, v0
	v_exp_f32_e32 v123, v0
	s_nop 0
	v_pk_add_f32 v[122:123], v[122:123], 1.0 op_sel_hi:[1,0]
	s_nop 0
	v_div_scale_f32 v0, s[20:21], v123, v123, 1.0
	v_rcp_f32_e32 v142, v0
	s_nop 0
	v_fma_f32 v143, -v0, v142, 1.0
	v_fmac_f32_e32 v142, v143, v142
	v_div_scale_f32 v143, vcc, 1.0, v123, 1.0
	v_mul_f32_e32 v156, v143, v142
	v_fma_f32 v157, -v0, v156, v143
	v_fmac_f32_e32 v156, v157, v142
	v_fma_f32 v0, -v0, v156, v143
	v_div_fmas_f32 v0, v0, v142, v156
	v_div_fixup_f32 v123, v0, v123, 1.0
	v_div_scale_f32 v0, s[20:21], v122, v122, 1.0
	v_rcp_f32_e32 v142, v0
	s_nop 0
	v_fma_f32 v143, -v0, v142, 1.0
	v_fmac_f32_e32 v142, v143, v142
	v_div_scale_f32 v143, vcc, 1.0, v122, 1.0
	v_mul_f32_e32 v156, v143, v142
	v_fma_f32 v157, -v0, v156, v143
	v_fmac_f32_e32 v156, v157, v142
	v_fma_f32 v0, -v0, v156, v143
	v_div_fmas_f32 v0, v0, v142, v156
	v_div_fixup_f32 v122, v0, v122, 1.0
	v_add_f32_e32 v0, v124, v144
	v_mul_f32_e32 v0, 0xbfb8aa3b, v0
	v_exp_f32_e32 v124, v0
	v_add_f32_e32 v0, v125, v145
	v_mul_f32_e32 v0, 0xbfb8aa3b, v0
	v_exp_f32_e32 v125, v0
	v_pk_fma_f32 v[122:123], v[126:127], v[122:123], v[152:153]
	v_pk_add_f32 v[124:125], v[124:125], 1.0 op_sel_hi:[1,0]
	s_nop 0
	v_div_scale_f32 v0, s[20:21], v125, v125, 1.0
	v_rcp_f32_e32 v126, v0
	s_nop 0
	v_fma_f32 v127, -v0, v126, 1.0
	v_fmac_f32_e32 v126, v127, v126
	v_div_scale_f32 v127, vcc, 1.0, v125, 1.0
	v_mul_f32_e32 v142, v127, v126
	v_fma_f32 v143, -v0, v142, v127
	v_fmac_f32_e32 v142, v143, v126
	v_fma_f32 v0, -v0, v142, v127
	v_div_fmas_f32 v0, v0, v126, v142
	v_div_fixup_f32 v125, v0, v125, 1.0
	v_div_scale_f32 v0, s[20:21], v124, v124, 1.0
	v_rcp_f32_e32 v126, v0
	v_readlane_b32 s20, v251, 32
	v_readlane_b32 s21, v251, 33
	v_fma_f32 v127, -v0, v126, 1.0
	v_fmac_f32_e32 v126, v127, v126
	v_div_scale_f32 v127, vcc, 1.0, v124, 1.0
	v_mul_f32_e32 v142, v127, v126
	v_fma_f32 v143, -v0, v142, v127
	v_fmac_f32_e32 v142, v143, v126
	v_fma_f32 v0, -v0, v142, v127
	v_div_fmas_f32 v0, v0, v126, v142
	v_div_fixup_f32 v124, v0, v124, 1.0
	v_lshl_add_u64 v[126:127], s[10:11], 0, v[146:147]
	v_pk_fma_f32 v[124:125], v[128:129], v[124:125], v[154:155]
	v_lshl_add_u64 v[128:129], v[126:127], 0, v[134:135]
	v_cndmask_b32_e64 v126, 0, 1, s[14:15]
	v_mov_b32_e32 v0, 0
	v_cmp_ne_u32_e64 s[42:43], 1, v126
	s_andn2_b64 vcc, exec, s[14:15]
	v_lshl_add_u64 v[126:127], v[130:131], 2, s[12:13]
	v_lshl_add_u64 v[140:141], v[140:141], 1, s[20:21]
	global_store_dwordx4 v[128:129], v[122:125], off
	s_cbranch_vccnz .LBB0_1346
	global_load_dwordx4 v[142:145], v[126:127], off
	s_waitcnt vmcnt(0)
	v_mul_f32_e32 v0, v122, v142
	v_mul_f32_e32 v142, v123, v143
	v_cvt_pk_bf16_f32 v142, v0, v142
	v_mul_f32_e32 v0, v124, v144
	v_mul_f32_e32 v143, v125, v145
	v_pk_mul_f32 v[122:123], v[122:123], v[122:123]
	v_cvt_pk_bf16_f32 v143, v0, v143
	v_pk_mul_f32 v[124:125], v[124:125], v[124:125]
	v_add_f32_e32 v0, v122, v123
	v_add_f32_e32 v0, v124, v0
	v_lshl_add_u64 v[144:145], v[130:131], 1, v[140:141]
	v_add_f32_e32 v0, v125, v0
	global_store_dwordx2 v[144:145], v[142:143], off
